# MLA interior attention loop: K / rope-K / V tiles staged HBM->LDS with global_load_lds (LDS-DMA) instead of VGPR loads + ds_write
# speedup vs baseline: 1.0044x; 1.0040x over previous
.LBB0_347:
	s_lshl_b64 s[0:1], s[50:51], 1
	s_mov_b64 s[2:3], s[10:11]
	s_add_u32 s10, s2, s0
	s_addc_u32 s11, s3, s1
	v_readlane_b32 s4, v255, 34
	v_readlane_b32 s5, v255, 35
	s_add_u32 s12, s4, s0
	s_addc_u32 s13, s5, s1
	s_lshl_b64 s[0:1], s[52:53], 1
	s_add_u32 s0, s2, s0
	s_addc_u32 s1, s3, s1
	v_lshl_add_u64 v[30:31], s[0:1], 0, v[112:113]
	s_mov_b32 s0, 2
	s_cmp_lt_u32 s22, 6
	v_cmp_gt_u32_e64 s[40:41], 32, v191
	v_add_u32_e32 v112, s14, v114
	v_lshl_add_u32 v198, v193, 2, s15
	v_lshl_add_u32 v1, v199, 2, s15
	s_waitcnt lgkmcnt(0)
	s_barrier
	s_cbranch_scc1 .LBB0_359
	v_add_u32_e32 v114, 0xc0, v112
	v_or_b32_e32 v170, 0xc0, v191
	s_mov_b32 s2, 5
	v_readfirstlane_b32 s100, v195
	s_branch .LBB0_350
.LBB0_349:
	v_pk_add_f32 v[66:67], v[66:67], v[200:201]
	v_pk_add_f32 v[68:69], v[68:69], v[6:7]
	v_pk_add_f32 v[70:71], v[70:71], v[8:9]
	v_pk_add_f32 v[72:73], v[72:73], v[10:11]
	v_pk_add_f32 v[74:75], v[74:75], v[12:13]
	v_pk_add_f32 v[76:77], v[76:77], v[14:15]
	v_pk_add_f32 v[78:79], v[78:79], v[16:17]
	v_add_f32_e32 v3, v64, v115
	v_add_f32_e32 v4, v65, v171
	v_pk_add_f32 v[66:67], v[66:67], v[68:69]
	v_pk_add_f32 v[70:71], v[70:71], v[72:73]
	v_pk_add_f32 v[74:75], v[74:75], v[76:77]
	v_add_f32_e32 v3, v3, v4
	v_pk_add_f32 v[66:67], v[66:67], v[70:71]
	v_pk_add_f32 v[74:75], v[74:75], v[78:79]
	v_pk_add_f32 v[66:67], v[66:67], v[74:75]
	v_add_f32_e32 v3, v3, v66
	v_add_f32_e32 v3, v3, v67
	s_add_i32 s2, s2, 1
	v_add_f32_e32 v163, v163, v3
	v_add_u32_e32 v114, 64, v114
	s_cmp_eq_u32 s22, s2
	v_add_u32_e32 v170, 64, v170
	s_waitcnt vmcnt(0)
	s_waitcnt lgkmcnt(0)
	s_barrier
	s_cbranch_scc1 .LBB0_358
.LBB0_350:
	s_add_i32 s0, s2, -1
	s_and_b32 s0, s0, 1
	s_mulk_i32 s0, 0x5100
	s_add_i32 s101, s100, s0
	v_ashrrev_i32_e32 v171, 31, v170
	v_lshlrev_b64 v[2:3], 11, v[170:171]
	s_mov_b32 m0, s101
	v_lshl_add_u64 v[2:3], s[10:11], 0, v[2:3]
	global_load_lds_dwordx4 v[2:3], off
	s_and_b64 vcc, exec, s[38:39]
	s_cbranch_vccnz .LBB0_352
	v_lshlrev_b64 v[2:3], 9, v[170:171]
	s_add_i32 m0, s101, 0x2000
	v_lshl_add_u64 v[2:3], s[12:13], 0, v[2:3]
	global_load_lds_dwordx4 v[2:3], off
.LBB0_352:
	s_add_i32 s0, s2, -1
	s_and_b32 s3, s0, 1
	s_xor_b32 s0, s3, 1
	s_mulk_i32 s0, 0x5100
	v_add_u32_e32 v84, s0, v197
	ds_read_b128 v[18:21], v84
	ds_read_b128 v[22:25], v84 offset:512
	v_ashrrev_i32_e32 v115, 31, v114
	s_waitcnt lgkmcnt(1)
	v_mfma_f32_32x32x16_bf16 v[2:17], v[18:21], v[116:119], v[96:111]
	s_waitcnt lgkmcnt(0)
	v_mfma_f32_32x32x16_bf16 v[64:79], v[22:25], v[116:119], v[96:111]
	ds_read_b128 v[18:21], v84 offset:2048
	ds_read_b128 v[22:25], v84 offset:2560
	s_waitcnt lgkmcnt(0)
	v_mfma_f32_32x32x16_bf16 v[64:79], v[22:25], v[120:123], v[64:79]
	v_mfma_f32_32x32x16_bf16 v[2:17], v[18:21], v[120:123], v[2:17]
	ds_read_b128 v[18:21], v84 offset:4096
	ds_read_b128 v[22:25], v84 offset:4608
	s_waitcnt lgkmcnt(0)
	v_mfma_f32_32x32x16_bf16 v[64:79], v[22:25], v[124:127], v[64:79]
	v_mfma_f32_32x32x16_bf16 v[2:17], v[18:21], v[124:127], v[2:17]
	ds_read_b128 v[18:21], v84 offset:6144
	ds_read_b128 v[22:25], v84 offset:6656
	s_waitcnt lgkmcnt(0)
	v_mfma_f32_32x32x16_bf16 v[64:79], v[22:25], v[128:131], v[64:79]
	v_lshlrev_b64 v[22:23], 11, v[114:115]
	s_add_i32 m0, s101, 0x2f80
	v_lshl_add_u64 v[26:27], v[30:31], 0, v[22:23]
	global_load_lds_dwordx4 v[26:27], off offset:128
	ds_read_b128 v[22:25], v84 offset:8704
	ds_read_b128 v[26:29], v84 offset:10240
	v_add_u32_e32 v115, s0, v196
	v_mfma_f32_32x32x16_bf16 v[2:17], v[18:21], v[128:131], v[2:17]
	ds_read_b128 v[18:21], v84 offset:8192
	s_waitcnt lgkmcnt(0)
	v_mfma_f32_32x32x16_bf16 v[2:17], v[18:21], v[132:135], v[2:17]
	ds_read_b64_tr_b16 v[152:153], v115 offset:12288
	ds_read_b64_tr_b16 v[154:155], v115 offset:12800
	ds_read_b64_tr_b16 v[88:89], v115 offset:13312
	ds_read_b64_tr_b16 v[90:91], v115 offset:13824
	ds_read_b64_tr_b16 v[80:81], v115 offset:14336
	ds_read_b64_tr_b16 v[82:83], v115 offset:14848
	ds_read_b64_tr_b16 v[18:19], v115 offset:15360
	ds_read_b64_tr_b16 v[20:21], v115 offset:15872
	ds_read_b128 v[200:203], v84 offset:10752
	v_mfma_f32_32x32x16_bf16 v[64:79], v[22:25], v[132:135], v[64:79]
	v_mfma_f32_32x32x16_bf16 v[2:17], v[26:29], v[136:139], v[2:17]
	ds_read_b64_tr_b16 v[92:93], v115 offset:16384
	ds_read_b64_tr_b16 v[94:95], v115 offset:16896
	ds_read_b64_tr_b16 v[84:85], v115 offset:17408
	ds_read_b64_tr_b16 v[86:87], v115 offset:17920
	ds_read_b64_tr_b16 v[26:27], v115 offset:18432
	ds_read_b64_tr_b16 v[28:29], v115 offset:18944
	ds_read_b64_tr_b16 v[22:23], v115 offset:19456
	ds_read_b64_tr_b16 v[24:25], v115 offset:19968
	s_waitcnt lgkmcnt(8)
	v_mfma_f32_32x32x16_bf16 v[64:79], v[200:203], v[136:139], v[64:79]
	v_max3_f32 v115, v2, v3, v64
	v_max3_f32 v171, v4, v5, v65
	v_max3_f32 v115, v115, v66, v67
	v_max3_f32 v171, v171, v8, v9
	v_max3_f32 v115, v115, v6, v7
	v_max3_f32 v171, v171, v70, v71
	v_max3_f32 v115, v115, v68, v69
	v_max3_f32 v171, v171, v12, v13
	v_max3_f32 v115, v115, v10, v11
	v_max3_f32 v171, v171, v74, v75
	v_max3_f32 v115, v115, v72, v73
	v_max3_f32 v171, v171, v16, v17
	v_max3_f32 v115, v115, v14, v15
	v_max3_f32 v171, v171, v78, v79
	v_max3_f32 v115, v115, v76, v77
	v_max_f32_e32 v115, v115, v171
	v_mov_b32_e32 v171, v115
	s_nop 1
	v_permlane32_swap_b32_e32 v115, v171
	v_max_f32_e32 v115, v115, v171
	v_cmp_lt_f32_e32 vcc, s75, v115
	s_cbranch_vccz .LBB0_356
	v_max_f32_e32 v96, v115, v115
	v_max_f32_e32 v98, 0, v96
	v_exp_f32_e64 v115, -v98
	s_and_saveexec_b64 s[0:1], s[40:41]
	ds_write_b32 v198, v115 offset:41472
	s_or_b64 exec, exec, s[0:1]
	s_waitcnt lgkmcnt(0)
	ds_read_b128 v[200:203], v1 offset:41472
	ds_read_b128 v[204:207], v1 offset:41504
	ds_read_b128 v[208:211], v1 offset:41536
	ds_read_b128 v[212:215], v1 offset:41568
	v_add_f32_e32 v0, v0, v98
	s_waitcnt lgkmcnt(0)
	v_xor_b32_e32 v96, 0x80000000, v0
	v_pk_add_f32 v[2:3], v[2:3], v[98:99] op_sel_hi:[1,0] neg_lo:[0,1] neg_hi:[0,1]
	v_pk_add_f32 v[64:65], v[64:65], v[98:99] op_sel_hi:[1,0] neg_lo:[0,1] neg_hi:[0,1]
	v_pk_add_f32 v[4:5], v[4:5], v[98:99] op_sel_hi:[1,0] neg_lo:[0,1] neg_hi:[0,1]
	v_pk_add_f32 v[66:67], v[66:67], v[98:99] op_sel_hi:[1,0] neg_lo:[0,1] neg_hi:[0,1]
	v_pk_add_f32 v[6:7], v[6:7], v[98:99] op_sel_hi:[1,0] neg_lo:[0,1] neg_hi:[0,1]
	v_pk_add_f32 v[68:69], v[68:69], v[98:99] op_sel_hi:[1,0] neg_lo:[0,1] neg_hi:[0,1]
	v_pk_add_f32 v[8:9], v[8:9], v[98:99] op_sel_hi:[1,0] neg_lo:[0,1] neg_hi:[0,1]
	v_pk_add_f32 v[70:71], v[70:71], v[98:99] op_sel_hi:[1,0] neg_lo:[0,1] neg_hi:[0,1]
	v_pk_add_f32 v[10:11], v[10:11], v[98:99] op_sel_hi:[1,0] neg_lo:[0,1] neg_hi:[0,1]
	v_pk_add_f32 v[72:73], v[72:73], v[98:99] op_sel_hi:[1,0] neg_lo:[0,1] neg_hi:[0,1]
	v_pk_add_f32 v[12:13], v[12:13], v[98:99] op_sel_hi:[1,0] neg_lo:[0,1] neg_hi:[0,1]
	v_pk_add_f32 v[74:75], v[74:75], v[98:99] op_sel_hi:[1,0] neg_lo:[0,1] neg_hi:[0,1]
	v_pk_add_f32 v[14:15], v[14:15], v[98:99] op_sel_hi:[1,0] neg_lo:[0,1] neg_hi:[0,1]
	v_pk_add_f32 v[76:77], v[76:77], v[98:99] op_sel_hi:[1,0] neg_lo:[0,1] neg_hi:[0,1]
	v_pk_add_f32 v[16:17], v[16:17], v[98:99] op_sel_hi:[1,0] neg_lo:[0,1] neg_hi:[0,1]
	v_pk_add_f32 v[78:79], v[78:79], v[98:99] op_sel_hi:[1,0] neg_lo:[0,1] neg_hi:[0,1]
	v_mov_b32_e32 v97, v96
	v_mov_b32_e32 v98, v96
	v_mov_b32_e32 v99, v96
	v_mov_b32_e32 v100, v96
	v_mov_b32_e32 v101, v96
	v_mov_b32_e32 v102, v96
	v_mov_b32_e32 v103, v96
	v_mov_b32_e32 v104, v96
	v_mov_b32_e32 v105, v96
	v_mov_b32_e32 v106, v96
	v_mov_b32_e32 v107, v96
	v_mov_b32_e32 v108, v96
	v_mov_b32_e32 v109, v96
	v_mov_b32_e32 v110, v96
	v_mov_b32_e32 v111, v96
	v_mul_f32_e32 v163, v163, v115
	s_waitcnt lgkmcnt(0)
	v_pk_mul_f32 v[46:47], v[46:47], v[214:215]
	v_pk_mul_f32 v[42:43], v[42:43], v[210:211]
	v_pk_mul_f32 v[38:39], v[38:39], v[206:207]
	v_pk_mul_f32 v[34:35], v[34:35], v[202:203]
	v_pk_mul_f32 v[44:45], v[44:45], v[212:213]
	v_pk_mul_f32 v[40:41], v[40:41], v[208:209]
	v_pk_mul_f32 v[36:37], v[36:37], v[204:205]
	v_pk_mul_f32 v[32:33], v[32:33], v[200:201]
	v_pk_mul_f32 v[62:63], v[62:63], v[214:215]
	v_pk_mul_f32 v[58:59], v[58:59], v[210:211]
	v_pk_mul_f32 v[54:55], v[54:55], v[206:207]
	v_pk_mul_f32 v[50:51], v[50:51], v[202:203]
	v_pk_mul_f32 v[60:61], v[60:61], v[212:213]
	v_pk_mul_f32 v[56:57], v[56:57], v[208:209]
	v_pk_mul_f32 v[52:53], v[52:53], v[204:205]
	v_pk_mul_f32 v[48:49], v[48:49], v[200:201]
.LBB0_356:
	v_exp_f32_e32 v115, v2
	v_exp_f32_e32 v171, v3
	v_exp_f32_e32 v200, v4
	v_exp_f32_e32 v201, v5
	v_exp_f32_e32 v6, v6
	v_exp_f32_e32 v7, v7
	v_exp_f32_e32 v8, v8
	v_exp_f32_e32 v9, v9
	v_cvt_pk_bf16_f32 v202, v115, v171
	v_cvt_pk_bf16_f32 v203, v200, v201
	v_cvt_pk_bf16_f32 v204, v6, v7
	v_cvt_pk_bf16_f32 v205, v8, v9
	v_exp_f32_e32 v10, v10
	v_exp_f32_e32 v11, v11
	v_exp_f32_e32 v12, v12
	v_exp_f32_e32 v13, v13
	v_exp_f32_e32 v14, v14
	v_exp_f32_e32 v15, v15
	v_exp_f32_e32 v16, v16
	v_exp_f32_e32 v17, v17
	v_mfma_f32_32x32x16_bf16 v[32:47], v[202:205], v[152:155], v[32:47]
	v_cvt_pk_bf16_f32 v206, v10, v11
	v_cvt_pk_bf16_f32 v207, v12, v13
	v_cvt_pk_bf16_f32 v208, v14, v15
	v_cvt_pk_bf16_f32 v209, v16, v17
	v_exp_f32_e32 v64, v64
	v_exp_f32_e32 v65, v65
	v_exp_f32_e32 v66, v66
	s_waitcnt lgkmcnt(6)
	v_mfma_f32_32x32x16_bf16 v[48:63], v[202:205], v[92:95], v[48:63]
	v_exp_f32_e32 v67, v67
	v_exp_f32_e32 v68, v68
	v_exp_f32_e32 v69, v69
	v_exp_f32_e32 v70, v70
	v_exp_f32_e32 v71, v71
	v_cvt_pk_bf16_f32 v210, v64, v65
	v_cvt_pk_bf16_f32 v211, v66, v67
	v_mfma_f32_32x32x16_bf16 v[32:47], v[206:209], v[88:91], v[32:47]
	v_cvt_pk_bf16_f32 v212, v68, v69
	v_cvt_pk_bf16_f32 v213, v70, v71
	v_exp_f32_e32 v72, v72
	v_exp_f32_e32 v73, v73
	v_exp_f32_e32 v74, v74
	v_exp_f32_e32 v75, v75
	v_exp_f32_e32 v76, v76
	s_waitcnt lgkmcnt(4)
	v_mfma_f32_32x32x16_bf16 v[48:63], v[206:209], v[84:87], v[48:63]
	v_exp_f32_e32 v77, v77
	v_exp_f32_e32 v78, v78
	v_exp_f32_e32 v79, v79
	v_cvt_pk_bf16_f32 v2, v72, v73
	v_cvt_pk_bf16_f32 v3, v74, v75
	v_cvt_pk_bf16_f32 v4, v76, v77
	v_cvt_pk_bf16_f32 v5, v78, v79
	v_mfma_f32_32x32x16_bf16 v[32:47], v[210:213], v[80:83], v[32:47]
	s_mulk_i32 s3, 0x5100
	s_and_b64 vcc, exec, s[38:39]
	s_waitcnt lgkmcnt(2)
	v_mfma_f32_32x32x16_bf16 v[48:63], v[210:213], v[26:29], v[48:63]
	v_mfma_f32_32x32x16_bf16 v[32:47], v[2:5], v[18:21], v[32:47]
	s_waitcnt lgkmcnt(0)
	v_mfma_f32_32x32x16_bf16 v[48:63], v[2:5], v[22:25], v[48:63]
	s_branch .LBB0_349

	.amdhsa_kernel _Z14fwd_megakernel6Params
		.amdhsa_group_segment_fixed_size 256
		.amdhsa_private_segment_fixed_size 0
		.amdhsa_kernarg_size 432
		.amdhsa_user_sgpr_count 2
		.amdhsa_user_sgpr_dispatch_ptr 0
		.amdhsa_user_sgpr_queue_ptr 0
		.amdhsa_user_sgpr_kernarg_segment_ptr 1
		.amdhsa_user_sgpr_dispatch_id 0
		.amdhsa_user_sgpr_kernarg_preload_length 0
		.amdhsa_user_sgpr_kernarg_preload_offset 0
		.amdhsa_user_sgpr_private_segment_size 0
		.amdhsa_uses_dynamic_stack 0
		.amdhsa_enable_private_segment 0
		.amdhsa_system_sgpr_workgroup_id_x 1
		.amdhsa_system_sgpr_workgroup_id_y 0
		.amdhsa_system_sgpr_workgroup_id_z 0
		.amdhsa_system_sgpr_workgroup_info 0
		.amdhsa_system_vgpr_workitem_id 2
		.amdhsa_next_free_vgpr 256
		.amdhsa_next_free_sgpr 102
		.amdhsa_accum_offset 256
		.amdhsa_reserve_vcc 1
		.amdhsa_float_round_mode_32 0
		.amdhsa_float_round_mode_16_64 0
		.amdhsa_float_denorm_mode_32 3
		.amdhsa_float_denorm_mode_16_64 3
		.amdhsa_dx10_clamp 1
		.amdhsa_ieee_mode 1
		.amdhsa_fp16_overflow 0
		.amdhsa_tg_split 0
		.amdhsa_exception_fp_ieee_invalid_op 0
		.amdhsa_exception_fp_denorm_src 0
		.amdhsa_exception_fp_ieee_div_zero 0
		.amdhsa_exception_fp_ieee_overflow 0
		.amdhsa_exception_fp_ieee_underflow 0
		.amdhsa_exception_fp_ieee_inexact 0
		.amdhsa_exception_int_div_zero 0
	.end_amdhsa_kernel

amdhsa.kernels:
  - .agpr_count:     0
    .args:
      - .offset:         0
        .size:           176
        .value_kind:     by_value
      - .offset:         176
        .size:           4
        .value_kind:     hidden_block_count_x
      - .offset:         180
        .size:           4
        .value_kind:     hidden_block_count_y
      - .offset:         184
        .size:           4
        .value_kind:     hidden_block_count_z
      - .offset:         188
        .size:           2
        .value_kind:     hidden_group_size_x
      - .offset:         190
        .size:           2
        .value_kind:     hidden_group_size_y
      - .offset:         192
        .size:           2
        .value_kind:     hidden_group_size_z
      - .offset:         194
        .size:           2
        .value_kind:     hidden_remainder_x
      - .offset:         196
        .size:           2
        .value_kind:     hidden_remainder_y
      - .offset:         198
        .size:           2
        .value_kind:     hidden_remainder_z
      - .offset:         216
        .size:           8
        .value_kind:     hidden_global_offset_x
      - .offset:         224
        .size:           8
        .value_kind:     hidden_global_offset_y
      - .offset:         232
        .size:           8
        .value_kind:     hidden_global_offset_z
      - .offset:         240
        .size:           2
        .value_kind:     hidden_grid_dims
      - .offset:         264
        .size:           8
        .value_kind:     hidden_multigrid_sync_arg
      - .offset:         296
        .size:           4
        .value_kind:     hidden_dynamic_lds_size
    .group_segment_fixed_size: 256
    .kernarg_segment_align: 8
    .kernarg_segment_size: 432
    .language:       OpenCL C
    .language_version:
      - 2
      - 0
    .max_flat_workgroup_size: 512
    .name:           _Z14fwd_megakernel6Params
    .private_segment_fixed_size: 0
    .sgpr_count:     108
    .sgpr_spill_count: 477
    .symbol:         _Z14fwd_megakernel6Params.kd
    .uniform_work_group_size: 1
    .uses_dynamic_stack: false
    .vgpr_count:     256
    .vgpr_spill_count: 0
    .wavefront_size: 64
